# k43 + seam FF1->FF2 as row-panel rendezvous (write-through HH stores); every WG takes its FF2 sample item after its unit behind a whole-grid wait
# baseline (speedup 1.0000x reference)
.LBB0_859:
	s_add_u32 s98, s10, 0x80
	s_addc_u32 s99, s11, 0
	v_lshl_add_u64 v[250:251], s[98:99], 0, v[136:137]
	s_add_i32 m0, s25, 0xc000
	s_nop 0
	global_load_lds_dwordx4 v[250:251], off
	v_lshl_add_u64 v[250:251], s[98:99], 0, v[138:139]
	s_add_i32 m0, s25, 0xe000
	s_nop 0
	global_load_lds_dwordx4 v[250:251], off
	v_lshl_add_u32 v152, s80, 8, v146
	v_lshl_or_b32 v144, s81, 8, v148
	v_ashrrev_i32_e32 v153, 31, v152
	v_max_f32_e32 v120, 0, v120
	v_ashrrev_i32_e32 v145, 31, v144
	v_lshlrev_b64 v[154:155], 13, v[152:153]
	v_max_f32_e32 v121, 0, v121
	v_max_f32_e32 v122, 0, v122
	v_max_f32_e32 v123, 0, v123
	v_lshl_add_u64 v[154:155], s[16:17], 0, v[154:155]
	v_lshlrev_b64 v[156:157], 1, v[144:145]
	v_max_f32_e32 v124, 0, v124
	v_mul_f32_e32 v120, v120, v120
	v_max_f32_e32 v125, 0, v125
	v_max_f32_e32 v126, 0, v126
	v_max_f32_e32 v127, 0, v127
	v_max_f32_e32 v112, 0, v112
	v_lshl_add_u64 v[144:145], v[154:155], 0, v[156:157]
	v_mul_f32_e32 v121, v121, v121
	v_mul_f32_e32 v122, v122, v122
	v_mul_f32_e32 v123, v123, v123
	v_cvt_pk_bf16_f32 v120, v120, v121
	v_max_f32_e32 v113, 0, v113
	v_max_f32_e32 v114, 0, v114
	v_mul_f32_e32 v124, v124, v124
	v_mul_f32_e32 v125, v125, v125
	v_mul_f32_e32 v126, v126, v126
	v_mul_f32_e32 v127, v127, v127
	v_cvt_pk_bf16_f32 v121, v122, v123
	v_cvt_pk_bf16_f32 v122, v124, v125
	v_cvt_pk_bf16_f32 v123, v126, v127
	global_store_dwordx4 v[144:145], v[120:123], off sc1
	s_nop 1
	v_mul_f32_e32 v120, v112, v112
	v_max_f32_e32 v112, 0, v117
	v_max_f32_e32 v116, 0, v116
	v_mul_f32_e32 v117, v113, v113
	v_max_f32_e32 v113, 0, v118
	v_mul_f32_e32 v118, v114, v114
	v_max_f32_e32 v114, 0, v119
	v_max_f32_e32 v115, 0, v115
	v_mul_f32_e32 v112, v112, v112
	v_mul_f32_e32 v116, v116, v116
	v_mul_f32_e32 v113, v113, v113
	v_mul_f32_e32 v114, v114, v114
	v_mul_f32_e32 v115, v115, v115
	v_cvt_pk_bf16_f32 v112, v116, v112
	v_max_f32_e32 v104, 0, v104
	v_cvt_pk_bf16_f32 v113, v113, v114
	v_cvt_pk_bf16_f32 v114, v120, v117
	v_cvt_pk_bf16_f32 v115, v118, v115
	global_store_dwordx4 v[144:145], v[112:115], off offset:256 sc1
	s_nop 1
	v_max_f32_e32 v105, 0, v105
	v_or_b32_e32 v112, 16, v152
	v_max_f32_e32 v106, 0, v106
	v_ashrrev_i32_e32 v113, 31, v112
	v_mul_f32_e32 v114, v104, v104
	v_max_f32_e32 v104, 0, v109
	v_lshlrev_b64 v[112:113], 13, v[112:113]
	v_max_f32_e32 v108, 0, v108
	v_mul_f32_e32 v109, v105, v105
	v_max_f32_e32 v105, 0, v110
	v_mul_f32_e32 v110, v106, v106
	v_max_f32_e32 v106, 0, v111
	v_max_f32_e32 v107, 0, v107
	v_lshl_add_u64 v[112:113], s[16:17], 0, v[112:113]
	v_mul_f32_e32 v104, v104, v104
	v_max_f32_e32 v96, 0, v96
	v_lshl_add_u64 v[112:113], v[112:113], 0, v[156:157]
	v_mul_f32_e32 v108, v108, v108
	v_mul_f32_e32 v105, v105, v105
	v_mul_f32_e32 v106, v106, v106
	v_mul_f32_e32 v107, v107, v107
	v_cvt_pk_bf16_f32 v104, v108, v104
	v_max_f32_e32 v97, 0, v97
	v_max_f32_e32 v98, 0, v98
	v_cvt_pk_bf16_f32 v105, v105, v106
	v_cvt_pk_bf16_f32 v106, v114, v109
	v_cvt_pk_bf16_f32 v107, v110, v107
	global_store_dwordx4 v[112:113], v[104:107], off sc1
	s_nop 1
	v_mul_f32_e32 v104, v96, v96
	v_max_f32_e32 v96, 0, v101
	v_max_f32_e32 v100, 0, v100
	v_mul_f32_e32 v101, v97, v97
	v_max_f32_e32 v97, 0, v102
	v_mul_f32_e32 v102, v98, v98
	v_max_f32_e32 v98, 0, v103
	v_max_f32_e32 v99, 0, v99
	v_mul_f32_e32 v96, v96, v96
	v_mul_f32_e32 v100, v100, v100
	v_mul_f32_e32 v97, v97, v97
	v_mul_f32_e32 v98, v98, v98
	v_mul_f32_e32 v99, v99, v99
	v_cvt_pk_bf16_f32 v96, v100, v96
	v_max_f32_e32 v88, 0, v88
	v_cvt_pk_bf16_f32 v97, v97, v98
	v_cvt_pk_bf16_f32 v98, v104, v101
	v_cvt_pk_bf16_f32 v99, v102, v99
	global_store_dwordx4 v[112:113], v[96:99], off offset:256 sc1
	s_nop 1
	v_max_f32_e32 v89, 0, v89
	v_or_b32_e32 v96, 32, v152
	v_max_f32_e32 v90, 0, v90
	v_ashrrev_i32_e32 v97, 31, v96
	v_mul_f32_e32 v98, v88, v88
	v_max_f32_e32 v88, 0, v93
	v_lshlrev_b64 v[96:97], 13, v[96:97]
	v_max_f32_e32 v92, 0, v92
	v_mul_f32_e32 v93, v89, v89
	v_max_f32_e32 v89, 0, v94
	v_mul_f32_e32 v94, v90, v90
	v_max_f32_e32 v90, 0, v95
	v_max_f32_e32 v91, 0, v91
	v_lshl_add_u64 v[96:97], s[16:17], 0, v[96:97]
	v_mul_f32_e32 v88, v88, v88
	v_max_f32_e32 v80, 0, v80
	v_lshl_add_u64 v[96:97], v[96:97], 0, v[156:157]
	v_mul_f32_e32 v92, v92, v92
	v_mul_f32_e32 v89, v89, v89
	v_mul_f32_e32 v90, v90, v90
	v_mul_f32_e32 v91, v91, v91
	v_cvt_pk_bf16_f32 v88, v92, v88
	v_max_f32_e32 v81, 0, v81
	v_max_f32_e32 v82, 0, v82
	v_cvt_pk_bf16_f32 v89, v89, v90
	v_cvt_pk_bf16_f32 v90, v98, v93
	v_cvt_pk_bf16_f32 v91, v94, v91
	global_store_dwordx4 v[96:97], v[88:91], off sc1
	s_nop 1
	v_mul_f32_e32 v88, v80, v80
	v_max_f32_e32 v80, 0, v85
	v_max_f32_e32 v84, 0, v84
	v_mul_f32_e32 v85, v81, v81
	v_max_f32_e32 v81, 0, v86
	v_mul_f32_e32 v86, v82, v82
	v_max_f32_e32 v82, 0, v87
	v_max_f32_e32 v83, 0, v83
	v_mul_f32_e32 v80, v80, v80
	v_mul_f32_e32 v84, v84, v84
	v_mul_f32_e32 v81, v81, v81
	v_mul_f32_e32 v82, v82, v82
	v_mul_f32_e32 v83, v83, v83
	v_cvt_pk_bf16_f32 v80, v84, v80
	v_max_f32_e32 v72, 0, v72
	v_cvt_pk_bf16_f32 v81, v81, v82
	v_cvt_pk_bf16_f32 v82, v88, v85
	v_cvt_pk_bf16_f32 v83, v86, v83
	global_store_dwordx4 v[96:97], v[80:83], off offset:256 sc1
	s_nop 1
	v_max_f32_e32 v73, 0, v73
	v_or_b32_e32 v80, 48, v152
	v_max_f32_e32 v74, 0, v74
	v_ashrrev_i32_e32 v81, 31, v80
	v_mul_f32_e32 v82, v72, v72
	v_max_f32_e32 v72, 0, v77
	v_lshlrev_b64 v[80:81], 13, v[80:81]
	v_max_f32_e32 v76, 0, v76
	v_mul_f32_e32 v77, v73, v73
	v_max_f32_e32 v73, 0, v78
	v_mul_f32_e32 v78, v74, v74
	v_max_f32_e32 v74, 0, v79
	v_max_f32_e32 v75, 0, v75
	v_lshl_add_u64 v[80:81], s[16:17], 0, v[80:81]
	v_mul_f32_e32 v72, v72, v72
	v_max_f32_e32 v64, 0, v64
	v_max_f32_e32 v65, 0, v65
	v_max_f32_e32 v66, 0, v66
	v_lshl_add_u64 v[80:81], v[80:81], 0, v[156:157]
	v_mul_f32_e32 v76, v76, v76
	v_mul_f32_e32 v73, v73, v73
	v_mul_f32_e32 v74, v74, v74
	v_mul_f32_e32 v75, v75, v75
	v_cvt_pk_bf16_f32 v72, v76, v72
	v_cvt_pk_bf16_f32 v73, v73, v74
	v_cvt_pk_bf16_f32 v74, v82, v77
	v_cvt_pk_bf16_f32 v75, v78, v75
	global_store_dwordx4 v[80:81], v[72:75], off sc1
	v_max_f32_e32 v68, 0, v68
	v_max_f32_e32 v67, 0, v67
	v_mul_f32_e32 v72, v64, v64
	v_max_f32_e32 v64, 0, v69
	v_mul_f32_e32 v69, v65, v65
	v_max_f32_e32 v65, 0, v70
	v_mul_f32_e32 v70, v66, v66
	v_max_f32_e32 v66, 0, v71
	v_mul_f32_e32 v64, v64, v64
	v_mul_f32_e32 v65, v65, v65
	v_mul_f32_e32 v66, v66, v66
	v_max_f32_e32 v56, 0, v56
	v_mul_f32_e32 v68, v68, v68
	v_mul_f32_e32 v67, v67, v67
	v_cvt_pk_bf16_f32 v64, v68, v64
	v_cvt_pk_bf16_f32 v65, v65, v66
	v_cvt_pk_bf16_f32 v66, v72, v69
	v_max_f32_e32 v57, 0, v57
	v_max_f32_e32 v58, 0, v58
	v_cvt_pk_bf16_f32 v67, v70, v67
	global_store_dwordx4 v[80:81], v[64:67], off offset:256 sc1
	s_nop 1
	v_max_f32_e32 v60, 0, v60
	v_mul_f32_e32 v66, v56, v56
	v_max_f32_e32 v56, 0, v61
	v_mul_f32_e32 v61, v57, v57
	v_max_f32_e32 v57, 0, v62
	v_mul_f32_e32 v62, v58, v58
	v_max_f32_e32 v58, 0, v63
	v_mul_f32_e32 v60, v60, v60
	v_mul_f32_e32 v56, v56, v56
	v_max_f32_e32 v59, 0, v59
	v_mul_f32_e32 v57, v57, v57
	v_mul_f32_e32 v58, v58, v58
	v_cvt_pk_bf16_f32 v56, v60, v56
	v_add_co_u32_e32 v60, vcc, s69, v144
	v_max_f32_e32 v48, 0, v48
	v_max_f32_e32 v49, 0, v49
	v_max_f32_e32 v50, 0, v50
	v_mul_f32_e32 v59, v59, v59
	v_cvt_pk_bf16_f32 v57, v57, v58
	v_cvt_pk_bf16_f32 v58, v66, v61
	v_addc_co_u32_e32 v61, vcc, 0, v145, vcc
	v_cvt_pk_bf16_f32 v59, v62, v59
	global_store_dwordx4 v[60:61], v[56:59], off sc1
	v_max_f32_e32 v52, 0, v52
	v_max_f32_e32 v51, 0, v51
	v_mul_f32_e32 v56, v48, v48
	v_max_f32_e32 v48, 0, v53
	v_mul_f32_e32 v53, v49, v49
	v_max_f32_e32 v49, 0, v54
	v_mul_f32_e32 v54, v50, v50
	v_max_f32_e32 v50, 0, v55
	v_mul_f32_e32 v48, v48, v48
	v_mul_f32_e32 v49, v49, v49
	v_mul_f32_e32 v50, v50, v50
	v_max_f32_e32 v40, 0, v40
	v_lshl_add_u64 v[64:65], v[144:145], 0, s[50:51]
	v_mul_f32_e32 v52, v52, v52
	v_mul_f32_e32 v51, v51, v51
	v_cvt_pk_bf16_f32 v48, v52, v48
	v_cvt_pk_bf16_f32 v49, v49, v50
	v_cvt_pk_bf16_f32 v50, v56, v53
	v_max_f32_e32 v41, 0, v41
	v_max_f32_e32 v42, 0, v42
	v_cvt_pk_bf16_f32 v51, v54, v51
	global_store_dwordx4 v[64:65], v[48:51], off offset:256 sc1
	s_nop 1
	v_max_f32_e32 v44, 0, v44
	v_mul_f32_e32 v50, v40, v40
	v_max_f32_e32 v40, 0, v45
	v_mul_f32_e32 v45, v41, v41
	v_max_f32_e32 v41, 0, v46
	v_mul_f32_e32 v46, v42, v42
	v_max_f32_e32 v42, 0, v47
	v_mul_f32_e32 v44, v44, v44
	v_mul_f32_e32 v40, v40, v40
	v_max_f32_e32 v43, 0, v43
	v_mul_f32_e32 v41, v41, v41
	v_mul_f32_e32 v42, v42, v42
	v_cvt_pk_bf16_f32 v40, v44, v40
	v_add_co_u32_e32 v44, vcc, s71, v144
	v_max_f32_e32 v32, 0, v32
	v_max_f32_e32 v33, 0, v33
	v_max_f32_e32 v34, 0, v34
	v_mul_f32_e32 v43, v43, v43
	v_cvt_pk_bf16_f32 v41, v41, v42
	v_cvt_pk_bf16_f32 v42, v50, v45
	v_addc_co_u32_e32 v45, vcc, 0, v145, vcc
	v_cvt_pk_bf16_f32 v43, v46, v43
	global_store_dwordx4 v[44:45], v[40:43], off sc1
	v_max_f32_e32 v36, 0, v36
	v_max_f32_e32 v35, 0, v35
	v_mul_f32_e32 v40, v32, v32
	v_max_f32_e32 v32, 0, v37
	v_mul_f32_e32 v37, v33, v33
	v_max_f32_e32 v33, 0, v38
	v_mul_f32_e32 v38, v34, v34
	v_max_f32_e32 v34, 0, v39
	v_mul_f32_e32 v32, v32, v32
	v_mul_f32_e32 v33, v33, v33
	v_mul_f32_e32 v34, v34, v34
	v_max_f32_e32 v24, 0, v24
	v_lshl_add_u64 v[48:49], v[144:145], 0, s[52:53]
	v_mul_f32_e32 v36, v36, v36
	v_mul_f32_e32 v35, v35, v35
	v_cvt_pk_bf16_f32 v32, v36, v32
	v_cvt_pk_bf16_f32 v33, v33, v34
	v_cvt_pk_bf16_f32 v34, v40, v37
	v_max_f32_e32 v25, 0, v25
	v_max_f32_e32 v26, 0, v26
	v_cvt_pk_bf16_f32 v35, v38, v35
	global_store_dwordx4 v[48:49], v[32:35], off offset:256 sc1
	s_nop 1
	v_max_f32_e32 v28, 0, v28
	v_mul_f32_e32 v34, v24, v24
	v_max_f32_e32 v24, 0, v29
	v_mul_f32_e32 v29, v25, v25
	v_max_f32_e32 v25, 0, v30
	v_mul_f32_e32 v30, v26, v26
	v_max_f32_e32 v26, 0, v31
	v_mul_f32_e32 v28, v28, v28
	v_mul_f32_e32 v24, v24, v24
	v_max_f32_e32 v27, 0, v27
	v_mul_f32_e32 v25, v25, v25
	v_mul_f32_e32 v26, v26, v26
	v_cvt_pk_bf16_f32 v24, v28, v24
	v_add_co_u32_e32 v28, vcc, s72, v144
	v_max_f32_e32 v16, 0, v16
	v_max_f32_e32 v17, 0, v17
	v_max_f32_e32 v18, 0, v18
	v_mul_f32_e32 v27, v27, v27
	v_cvt_pk_bf16_f32 v25, v25, v26
	v_cvt_pk_bf16_f32 v26, v34, v29
	v_addc_co_u32_e32 v29, vcc, 0, v145, vcc
	v_cvt_pk_bf16_f32 v27, v30, v27
	global_store_dwordx4 v[28:29], v[24:27], off sc1
	v_max_f32_e32 v20, 0, v20
	v_max_f32_e32 v19, 0, v19
	v_mul_f32_e32 v24, v16, v16
	v_max_f32_e32 v16, 0, v21
	v_mul_f32_e32 v21, v17, v17
	v_max_f32_e32 v17, 0, v22
	v_mul_f32_e32 v22, v18, v18
	v_max_f32_e32 v18, 0, v23
	v_mul_f32_e32 v16, v16, v16
	v_mul_f32_e32 v17, v17, v17
	v_mul_f32_e32 v18, v18, v18
	v_max_f32_e32 v8, 0, v8
	v_lshl_add_u64 v[32:33], v[144:145], 0, s[54:55]
	v_mul_f32_e32 v20, v20, v20
	v_mul_f32_e32 v19, v19, v19
	v_cvt_pk_bf16_f32 v16, v20, v16
	v_cvt_pk_bf16_f32 v17, v17, v18
	v_cvt_pk_bf16_f32 v18, v24, v21
	v_max_f32_e32 v9, 0, v9
	v_max_f32_e32 v10, 0, v10
	v_cvt_pk_bf16_f32 v19, v22, v19
	global_store_dwordx4 v[32:33], v[16:19], off offset:256 sc1
	s_nop 1
	v_max_f32_e32 v12, 0, v12
	v_mul_f32_e32 v18, v8, v8
	v_max_f32_e32 v8, 0, v13
	v_mul_f32_e32 v13, v9, v9
	v_max_f32_e32 v9, 0, v14
	v_mul_f32_e32 v14, v10, v10
	v_max_f32_e32 v10, 0, v15
	v_mul_f32_e32 v12, v12, v12
	v_mul_f32_e32 v8, v8, v8
	v_max_f32_e32 v11, 0, v11
	v_mul_f32_e32 v9, v9, v9
	v_mul_f32_e32 v10, v10, v10
	v_cvt_pk_bf16_f32 v8, v12, v8
	v_add_co_u32_e32 v12, vcc, s75, v144
	v_max_f32_e32 v0, 0, v0
	v_max_f32_e32 v1, 0, v1
	v_max_f32_e32 v2, 0, v2
	v_mul_f32_e32 v11, v11, v11
	v_cvt_pk_bf16_f32 v9, v9, v10
	v_cvt_pk_bf16_f32 v10, v18, v13
	v_addc_co_u32_e32 v13, vcc, 0, v145, vcc
	v_cvt_pk_bf16_f32 v11, v14, v11
	global_store_dwordx4 v[12:13], v[8:11], off sc1
	v_max_f32_e32 v3, 0, v3
	v_max_f32_e32 v4, 0, v4
	v_mul_f32_e32 v8, v0, v0
	v_max_f32_e32 v0, 0, v5
	v_mul_f32_e32 v5, v1, v1
	v_max_f32_e32 v1, 0, v6
	v_mul_f32_e32 v6, v2, v2
	v_max_f32_e32 v2, 0, v7
	v_lshl_add_u64 v[16:17], v[144:145], 0, s[56:57]
	v_mul_f32_e32 v0, v0, v0
	v_mul_f32_e32 v1, v1, v1
	v_mul_f32_e32 v2, v2, v2
	v_mul_f32_e32 v3, v3, v3
	s_and_b64 vcc, exec, s[8:9]
	s_mov_b64 s[8:9], -1
	v_mul_f32_e32 v4, v4, v4
	v_cvt_pk_bf16_f32 v0, v4, v0
	v_cvt_pk_bf16_f32 v1, v1, v2
	v_cvt_pk_bf16_f32 v2, v8, v5
	v_cvt_pk_bf16_f32 v3, v6, v3
	global_store_dwordx4 v[16:17], v[0:3], off offset:256 sc1
	s_cbranch_vccnz .LBB0_843
	s_andn2_b64 vcc, exec, s[42:43]
	s_cbranch_vccnz .LBB0_842
	s_barrier
	s_branch .LBB0_842

.LBB0_882:
	v_add_u32_e32 v136, s8, v6
	v_ashrrev_i32_e32 v137, 31, v136
	v_lshlrev_b64 v[136:137], 11, v[136:137]
	v_lshl_add_u64 v[160:161], v[2:3], 0, v[136:137]
	global_load_dwordx4 v[8:11], v[0:1], off
	global_load_dwordx4 v[12:15], v[0:1], off offset:64
	global_load_dwordx4 v[16:19], v[0:1], off offset:128
	global_load_dwordx4 v[20:23], v[0:1], off offset:192
	global_load_dwordx4 v[24:27], v[0:1], off offset:256
	global_load_dwordx4 v[28:31], v[0:1], off offset:320
	global_load_dwordx4 v[32:35], v[0:1], off offset:384
	global_load_dwordx4 v[36:39], v[0:1], off offset:448
	global_load_dwordx4 v[40:43], v[0:1], off offset:512
	global_load_dwordx4 v[44:47], v[0:1], off offset:576
	global_load_dwordx4 v[48:51], v[0:1], off offset:640
	global_load_dwordx4 v[52:55], v[0:1], off offset:704
	global_load_dwordx4 v[56:59], v[0:1], off offset:768
	global_load_dwordx4 v[60:63], v[0:1], off offset:832
	global_load_dwordx4 v[64:67], v[0:1], off offset:896
	global_load_dwordx4 v[68:71], v[0:1], off offset:960
	global_load_dwordx4 v[72:75], v[0:1], off offset:1024
	global_load_dwordx4 v[76:79], v[0:1], off offset:1088
	global_load_dwordx4 v[80:83], v[0:1], off offset:1152
	global_load_dwordx4 v[84:87], v[0:1], off offset:1216
	global_load_dwordx4 v[88:91], v[0:1], off offset:1280
	global_load_dwordx4 v[92:95], v[0:1], off offset:1344
	global_load_dwordx4 v[96:99], v[0:1], off offset:1408
	global_load_dwordx4 v[100:103], v[0:1], off offset:1472
	global_load_dwordx4 v[104:107], v[0:1], off offset:1536
	global_load_dwordx4 v[108:111], v[0:1], off offset:1600
	global_load_dwordx4 v[112:115], v[0:1], off offset:1664
	global_load_dwordx4 v[116:119], v[0:1], off offset:1728
	global_load_dwordx4 v[120:123], v[0:1], off offset:1792
	global_load_dwordx4 v[124:127], v[0:1], off offset:1856
	global_load_dwordx4 v[128:131], v[0:1], off offset:1920
	global_load_dwordx4 v[132:135], v[0:1], off offset:1984
	global_load_dwordx4 v[136:139], v[160:161], off
	global_load_dwordx4 v[140:143], v[160:161], off offset:64
	global_load_dwordx4 v[144:147], v[160:161], off offset:128
	global_load_dwordx4 v[148:151], v[160:161], off offset:192
	global_load_dwordx4 v[152:155], v[160:161], off offset:256
	global_load_dwordx4 v[156:159], v[160:161], off offset:320
	s_ashr_i32 s9, s8, 31
	s_add_i32 s14, s14, s33
	s_waitcnt vmcnt(5)
	v_mfma_f32_16x16x32_bf16 v[8:11], v[8:11], v[136:139], 0
	global_load_dwordx4 v[136:139], v[160:161], off offset:384
	s_waitcnt vmcnt(5)
	v_mfma_f32_16x16x32_bf16 v[8:11], v[12:15], v[140:143], v[8:11]
	global_load_dwordx4 v[12:15], v[160:161], off offset:448
	s_waitcnt vmcnt(5)
	v_mfma_f32_16x16x32_bf16 v[8:11], v[16:19], v[144:147], v[8:11]
	global_load_dwordx4 v[16:19], v[160:161], off offset:512
	s_waitcnt vmcnt(5)
	v_mfma_f32_16x16x32_bf16 v[8:11], v[20:23], v[148:151], v[8:11]
	global_load_dwordx4 v[20:23], v[160:161], off offset:576
	s_waitcnt vmcnt(5)
	v_mfma_f32_16x16x32_bf16 v[8:11], v[24:27], v[152:155], v[8:11]
	global_load_dwordx4 v[24:27], v[160:161], off offset:640
	s_waitcnt vmcnt(5)
	v_mfma_f32_16x16x32_bf16 v[8:11], v[28:31], v[156:159], v[8:11]
	global_load_dwordx4 v[28:31], v[160:161], off offset:704
	s_waitcnt vmcnt(5)
	v_mfma_f32_16x16x32_bf16 v[8:11], v[32:35], v[136:139], v[8:11]
	global_load_dwordx4 v[32:35], v[160:161], off offset:768
	s_waitcnt vmcnt(5)
	v_mfma_f32_16x16x32_bf16 v[8:11], v[36:39], v[12:15], v[8:11]
	global_load_dwordx4 v[12:15], v[160:161], off offset:832
	s_waitcnt vmcnt(5)
	v_mfma_f32_16x16x32_bf16 v[8:11], v[40:43], v[16:19], v[8:11]
	global_load_dwordx4 v[16:19], v[160:161], off offset:896
	s_waitcnt vmcnt(5)
	v_mfma_f32_16x16x32_bf16 v[8:11], v[44:47], v[20:23], v[8:11]
	global_load_dwordx4 v[20:23], v[160:161], off offset:960
	s_waitcnt vmcnt(5)
	v_mfma_f32_16x16x32_bf16 v[8:11], v[48:51], v[24:27], v[8:11]
	global_load_dwordx4 v[24:27], v[160:161], off offset:1024
	s_waitcnt vmcnt(5)
	v_mfma_f32_16x16x32_bf16 v[8:11], v[52:55], v[28:31], v[8:11]
	global_load_dwordx4 v[28:31], v[160:161], off offset:1088
	s_waitcnt vmcnt(5)
	v_mfma_f32_16x16x32_bf16 v[8:11], v[56:59], v[32:35], v[8:11]
	global_load_dwordx4 v[32:35], v[160:161], off offset:1152
	s_waitcnt vmcnt(5)
	v_mfma_f32_16x16x32_bf16 v[8:11], v[60:63], v[12:15], v[8:11]
	global_load_dwordx4 v[12:15], v[160:161], off offset:1216
	s_waitcnt vmcnt(5)
	v_mfma_f32_16x16x32_bf16 v[8:11], v[64:67], v[16:19], v[8:11]
	global_load_dwordx4 v[16:19], v[160:161], off offset:1280
	s_waitcnt vmcnt(5)
	v_mfma_f32_16x16x32_bf16 v[8:11], v[68:71], v[20:23], v[8:11]
	global_load_dwordx4 v[20:23], v[160:161], off offset:1344
	s_waitcnt vmcnt(5)
	v_mfma_f32_16x16x32_bf16 v[8:11], v[72:75], v[24:27], v[8:11]
	global_load_dwordx4 v[24:27], v[160:161], off offset:1408
	s_waitcnt vmcnt(5)
	v_mfma_f32_16x16x32_bf16 v[8:11], v[76:79], v[28:31], v[8:11]
	global_load_dwordx4 v[28:31], v[160:161], off offset:1472
	s_waitcnt vmcnt(5)
	v_mfma_f32_16x16x32_bf16 v[8:11], v[80:83], v[32:35], v[8:11]
	global_load_dwordx4 v[32:35], v[160:161], off offset:1536
	s_waitcnt vmcnt(5)
	v_mfma_f32_16x16x32_bf16 v[8:11], v[84:87], v[12:15], v[8:11]
	global_load_dwordx4 v[12:15], v[160:161], off offset:1600
	s_waitcnt vmcnt(5)
	v_mfma_f32_16x16x32_bf16 v[8:11], v[88:91], v[16:19], v[8:11]
	global_load_dwordx4 v[16:19], v[160:161], off offset:1664
	s_waitcnt vmcnt(5)
	v_mfma_f32_16x16x32_bf16 v[8:11], v[92:95], v[20:23], v[8:11]
	global_load_dwordx4 v[20:23], v[160:161], off offset:1728
	s_waitcnt vmcnt(5)
	v_mfma_f32_16x16x32_bf16 v[8:11], v[96:99], v[24:27], v[8:11]
	global_load_dwordx4 v[24:27], v[160:161], off offset:1792
	s_waitcnt vmcnt(5)
	v_mfma_f32_16x16x32_bf16 v[8:11], v[100:103], v[28:31], v[8:11]
	global_load_dwordx4 v[28:31], v[160:161], off offset:1856
	s_waitcnt vmcnt(5)
	v_mfma_f32_16x16x32_bf16 v[8:11], v[104:107], v[32:35], v[8:11]
	global_load_dwordx4 v[32:35], v[160:161], off offset:1920
	s_waitcnt vmcnt(5)
	v_mfma_f32_16x16x32_bf16 v[8:11], v[108:111], v[12:15], v[8:11]
	global_load_dwordx4 v[12:15], v[160:161], off offset:1984
	s_waitcnt vmcnt(5)
	v_mfma_f32_16x16x32_bf16 v[8:11], v[112:115], v[16:19], v[8:11]
	v_lshl_add_u64 v[16:17], s[8:9], 1, v[4:5]
	v_add_co_u32_e32 v18, vcc, s12, v16
	s_waitcnt vmcnt(4)
	v_mfma_f32_16x16x32_bf16 v[8:11], v[116:119], v[20:23], v[8:11]
	v_addc_co_u32_e32 v19, vcc, 0, v17, vcc
	v_add_co_u32_e32 v20, vcc, s13, v16
	s_waitcnt vmcnt(3)
	v_mfma_f32_16x16x32_bf16 v[8:11], v[120:123], v[24:27], v[8:11]
	s_add_i32 s8, s8, s10
	v_addc_co_u32_e32 v21, vcc, 0, v17, vcc
	s_waitcnt vmcnt(2)
	v_mfma_f32_16x16x32_bf16 v[8:11], v[124:127], v[28:31], v[8:11]
	s_cmpk_gt_i32 s14, 0xff
	v_add_co_u32_e32 v22, vcc, 0x6000, v16
	s_waitcnt vmcnt(1)
	v_mfma_f32_16x16x32_bf16 v[8:11], v[128:131], v[32:35], v[8:11]
	v_addc_co_u32_e32 v23, vcc, 0, v17, vcc
	s_waitcnt vmcnt(0)
	v_mfma_f32_16x16x32_bf16 v[8:11], v[132:135], v[12:15], v[8:11]
	s_nop 7
	v_max_f32_e32 v7, v8, v8
	v_max_f32_e32 v8, v9, v9
	v_max_f32_e32 v9, v10, v10
	v_max_f32_e32 v10, v11, v11
	v_max_f32_e32 v7, 0, v7
	v_max_f32_e32 v8, 0, v8
	v_max_f32_e32 v9, 0, v9
	v_max_f32_e32 v10, 0, v10
	v_mul_f32_e32 v7, v7, v7
	v_mul_f32_e32 v8, v8, v8
	v_mul_f32_e32 v9, v9, v9
	v_mul_f32_e32 v10, v10, v10
	v_bfe_u32 v11, v7, 16, 1
	v_bfe_u32 v12, v8, 16, 1
	v_bfe_u32 v13, v9, 16, 1
	v_bfe_u32 v14, v10, 16, 1
	v_add3_u32 v7, v7, v11, s11
	v_add3_u32 v8, v8, v12, s11
	v_add3_u32 v9, v9, v13, s11
	v_add3_u32 v10, v10, v14, s11
	global_store_short_d16_hi v[16:17], v7, off sc1
	global_store_short_d16_hi v[18:19], v8, off sc1
	global_store_short_d16_hi v[20:21], v9, off sc1
	global_store_short_d16_hi v[22:23], v10, off sc1
	s_cbranch_scc0 .LBB0_882
.LBB0_883:
	s_waitcnt vmcnt(0)
	s_and_b64 vcc, exec, s[94:95]
	s_barrier
	s_cbranch_vccnz .LBB0_937
	v_mbcnt_lo_u32_b32 v0, -1, 0
	v_mbcnt_hi_u32_b32 v0, -1, v0
	s_nop 0
	v_cmp_eq_u32_e32 vcc, 0, v0
	s_and_saveexec_b64 s[8:9], vcc
	s_cbranch_execz .LBB0_936
	s_and_b32 s10, s2, 7
	s_lshl_b32 s10, s10, 3
	s_bfe_u32 s11, s2, 0x30003
	s_or_b32 s10, s10, s11
	s_lshl_b32 s10, s10, 8
	s_add_u32 s12, s0, 0x1c000
	s_addc_u32 s13, s1, 0
	s_add_u32 s12, s12, s10
	s_addc_u32 s13, s13, 0
	s_add_u32 s14, s0, 0x28600
	s_addc_u32 s15, s1, 0
	v_mov_b32_e32 v0, 0
	v_mov_b32_e32 v1, 1
	s_waitcnt vmcnt(0) lgkmcnt(0)
	global_atomic_add v0, v1, s[12:13]
	global_atomic_add v0, v1, s[14:15]
	s_mov_b32 s16, 0

.Lr8_panel_ok:
.Lr8_acq:
	buffer_inv sc1
	s_waitcnt vmcnt(0)

.LBB0_939:
	s_load_dword s8, s[10:11], 0xec
	s_waitcnt lgkmcnt(0)
	s_add_u32 s16, s18, 0x1000000
	s_addc_u32 s17, s19, 0
	s_mov_b64 s[22:23], -1
	s_and_b64 vcc, exec, s[22:23]
	s_cbranch_vccnz .LBB0_943
	v_mbcnt_lo_u32_b32 v0, -1, 0
	v_mbcnt_hi_u32_b32 v0, -1, v0
	s_and_b64 vcc, exec, s[4:5]
	v_add_u32_e32 v1, s73, v0
	s_cbranch_vccnz .LBB0_943
	v_and_b32_e32 v0, 15, v1
	v_or_b32_e32 v2, s70, v0
	v_mov_b32_e32 v3, 0
	v_lshlrev_b64 v[4:5], 13, v[2:3]
	v_lshrrev_b32_e32 v2, 1, v1
	v_and_b32_e32 v6, 24, v2
	v_lshl_add_u64 v[4:5], s[18:19], 0, v[4:5]
	v_lshlrev_b32_e32 v2, 1, v6
	v_lshl_add_u64 v[4:5], v[4:5], 0, v[2:3]
	s_mov_b64 s[12:13], 0x1c400000
	v_lshl_add_u64 v[4:5], v[4:5], 0, s[12:13]
	s_add_u32 s12, s18, 0x29900000
	v_lshrrev_b32_e32 v1, 2, v1
	s_addc_u32 s13, s19, 0
	v_and_or_b32 v1, v1, 12, s70
	s_lshl_b32 s9, s92, 2
	s_lshl_b32 s14, s33, 2
	s_mov_b32 s35, 0
	v_lshlrev_b32_e32 v6, 1, v6
	v_mov_b32_e32 v7, v3
	v_lshlrev_b32_e32 v8, 2, v0
	v_mov_b32_e32 v9, v3
	s_movk_i32 s15, 0x1000
	s_mov_b32 s24, s92

.LBB0_1001:
	s_cmp_lg_u32 s93, 0
	s_cbranch_scc1 .Lr8s_done
	v_mbcnt_lo_u32_b32 v0, -1, 0
	v_mbcnt_hi_u32_b32 v0, -1, v0
	s_nop 0
	v_cmp_eq_u32_e32 vcc, 0, v0
	s_and_saveexec_b64 s[8:9], vcc
	s_cbranch_execz .Lr8s_x
	s_add_u32 s14, s0, 0x28600
	s_addc_u32 s15, s1, 0
	v_mov_b32_e32 v0, 0
	s_mov_b32 s10, 0
.Lr8s_wait:
	global_load_dword v2, v0, s[14:15] sc1
	s_waitcnt vmcnt(0)
	v_readfirstlane_b32 s11, v2
	s_cmp_ge_u32 s11, s33
	s_cbranch_scc1 .Lr8s_acq
	s_sleep 1
	s_add_i32 s10, s10, 1
	s_cmp_lt_u32 s10, 0x40001
	s_cbranch_scc1 .Lr8s_wait

.Lr8s_done:
	s_barrier
	s_andn2_b64 vcc, exec, s[22:23]
	s_cbranch_vccnz .LBB0_1005
	v_mbcnt_lo_u32_b32 v0, -1, 0
	v_mbcnt_hi_u32_b32 v0, -1, v0
	s_and_b64 vcc, exec, s[4:5]
	v_add_u32_e32 v1, s73, v0
	s_cbranch_vccnz .LBB0_1005
	v_and_b32_e32 v0, 15, v1
	v_or_b32_e32 v2, s70, v0
	v_mov_b32_e32 v3, 0
	v_lshlrev_b64 v[4:5], 13, v[2:3]
	v_lshrrev_b32_e32 v2, 1, v1
	v_and_b32_e32 v6, 24, v2
	v_lshl_add_u64 v[4:5], s[18:19], 0, v[4:5]
	v_lshlrev_b32_e32 v2, 1, v6
	v_lshl_add_u64 v[4:5], v[4:5], 0, v[2:3]
	s_mov_b64 s[4:5], 0x1c400000
	v_lshl_add_u64 v[4:5], v[4:5], 0, s[4:5]
	s_add_u32 s4, s18, 0x29900000
	v_lshrrev_b32_e32 v1, 2, v1
	s_addc_u32 s5, s19, 0
	v_and_or_b32 v1, v1, 12, s70
	s_lshl_b32 s12, s92, 2
	s_lshl_b32 s13, s33, 2
	s_mov_b32 s9, 0
	v_lshlrev_b32_e32 v6, 1, v6
	v_mov_b32_e32 v7, v3
	v_lshlrev_b32_e32 v8, 2, v0
	v_mov_b32_e32 v9, v3
	s_movk_i32 s14, 0x1000
	s_mov_b32 s15, s92
